# merge branch GEMM (K=512, variable row pitch) K loop also on the HBM->LDS DMA loop
# speedup vs baseline: 1.1280x; 1.0177x over previous
; DEV int tid_() { int t = threadIdx.x; asm volatile("" : "+v"(t)); return t; }
; template <int NI, bool DEEP = true>
; DEV void gemm_tile(f32x16 (&acc)[2][NI], const bf16* __restrict__ A, int lda, const bf16* __restrict__ Bt, int ldb,
;                    int K, bf16* sA, bf16* sB) {
;   int tid = tid_(), lane = tid & 63, wave = tid >> 6;
;   int wm = wave >> 1, wn = wave & 1;
;   int lr = tid >> 3, lc = (tid & 7) * 8;
;   const bf16* Ap = A + (size_t)lr * lda + lc;
;   const bf16* Bp = Bt + (size_t)lr * ldb + lc;
;   u32x4 ra0[4], rb0[2 * NI], ra1[4], rb1[2 * NI];
; __device__ void phase_merge(PRef p, int l, const bf16* H2, bf16* M, bf16* sA, bf16* sB) {
;     ...
;       const bf16* U = n == 0 ? p.HY : (n == 1 ? p.ZB : p.ZC);
;       int ldu = n == 2 ? 768 : 512;
;       uint32_t gp[2][2][8];
;       {
;         f32x16 a2[2][2];
;         zero_acc<2>(a2);
;         gemm_tile<2>(a2, H2 + (size_t)rt * 128 * 1024, 1024, p.WT3 + ((size_t)n * 1024 + ct * 128) * 1024, 1024, 1024, sA, sB);
; #pragma unroll
;         for (int a = 0; a < 2; a++)
; #pragma unroll
;           for (int bb = 0; bb < 2; bb++)
; #pragma unroll
;             for (int r = 0; r < 8; r++) {
;               float g0 = __fdividef(1.f, 1.f + __expf(-a2[a][bb][2 * r]));
;               float g1 = __fdividef(1.f, 1.f + __expf(-a2[a][bb][2 * r + 1]));
;               gp[a][bb][r] = pack2(g0, g1);
;             }
;       }
;       f32x16 a1[2][2];
;       zero_acc<2>(a1);
;       gemm_tile<2, false>(a1, U + (size_t)rt * 128 * ldu, ldu, p.WBO + ((size_t)n * 1024 + ct * 128) * 512, 512, 512, sA, sB);
.LBB0_968:
	s_cmp_eq_u32 s95, 2
	s_cselect_b32 s61, s83, 0x200
	s_mul_i32 s0, s15, s61
	s_mul_hi_u32 s1, s14, s61
	s_add_i32 s1, s1, s0
	s_mul_i32 s0, s14, s61
	s_lshl_b64 s[0:1], s[0:1], 1
	s_add_u32 s98, s54, s0
	s_addc_u32 s99, s55, s1
	s_lshl_b64 s[34:35], s[56:57], 10
	s_add_u32 s100, s12, s34
	s_addc_u32 s101, s13, s35
	s_lshl_b32 s56, s61, 1
	s_lshl_b32 s0, s61, 4
	v_and_b32_e32 v0, 63, v196
	v_lshrrev_b32_e32 v1, 6, v196
	v_lshrrev_b32_e32 v2, 3, v0
	v_readfirstlane_b32 s28, v1
	v_lshrrev_b32_e32 v146, 1, v2
	v_and_b32_e32 v147, 7, v0
	v_xor_b32_e32 v146, v147, v146
	v_lshlrev_b32_e32 v146, 4, v146
	v_mul_lo_u32 v134, v2, s56
	v_or_b32_e32 v134, v134, v146
	v_xor_b32_e32 v135, 64, v134
	v_lshl_or_b32 v136, v2, 10, v146
	v_xor_b32_e32 v137, 64, v136
	v_lshrrev_b32_e32 v146, 5, v0
	v_bfe_u32 v147, v0, 1, 3
	v_and_b32_e32 v2, 31, v0
	v_lshrrev_b32_e32 v0, 1, v1
	v_and_b32_e32 v1, 1, v1
	v_lshl_add_u32 v0, v0, 6, v2
	v_lshl_add_u32 v1, v1, 6, v2
	v_lshlrev_b32_e32 v0, 7, v0
	v_lshlrev_b32_e32 v1, 7, v1
	v_add_u32_e32 v1, 0x4000, v1
	v_add_u32_e32 v2, 0, v146
	v_xor_b32_e32 v2, v2, v147
	v_lshl_add_u32 v138, v2, 4, v0
	v_lshl_add_u32 v142, v2, 4, v1
	v_add_u32_e32 v2, 2, v146
	v_xor_b32_e32 v2, v2, v147
	v_lshl_add_u32 v139, v2, 4, v0
	v_lshl_add_u32 v143, v2, 4, v1
	v_add_u32_e32 v2, 4, v146
	v_xor_b32_e32 v2, v2, v147
	v_lshl_add_u32 v140, v2, 4, v0
	v_lshl_add_u32 v144, v2, 4, v1
	v_add_u32_e32 v2, 6, v146
	v_xor_b32_e32 v2, v2, v147
	v_lshl_add_u32 v141, v2, 4, v0
	v_lshl_add_u32 v145, v2, 4, v1
	s_lshl_b32 s1, s56, 5
	s_mul_i32 s1, s1, s28
	s_add_u32 s98, s98, s1
	s_addc_u32 s99, s99, 0
	s_lshl_b32 s1, s28, 15
	s_add_u32 s100, s100, s1
	s_addc_u32 s101, s101, 0
	s_lshl_b32 s28, s28, 12
	s_waitcnt lgkmcnt(0)
	s_barrier
	s_add_u32 m0, s28, 0x0
	s_nop 0
	global_load_lds_dwordx4 v134, s[98:99]
	s_add_u32 m0, s28, 0x400
	s_add_u32 s34, s98, s0
	s_addc_u32 s35, s99, 0
	global_load_lds_dwordx4 v135, s[34:35]
	s_add_u32 m0, s28, 0x800
	s_add_u32 s34, s34, s0
	s_addc_u32 s35, s35, 0
	global_load_lds_dwordx4 v134, s[34:35]
	s_add_u32 m0, s28, 0xc00
	s_add_u32 s34, s34, s0
	s_addc_u32 s35, s35, 0
	global_load_lds_dwordx4 v135, s[34:35]
	s_add_u32 m0, s28, 0x4000
	s_nop 0
	global_load_lds_dwordx4 v136, s[100:101]
	s_add_u32 m0, s28, 0x4400
	s_add_u32 s34, s100, 0x2000
	s_addc_u32 s35, s101, 0
	global_load_lds_dwordx4 v137, s[34:35]
	s_add_u32 m0, s28, 0x4800
	s_add_u32 s34, s100, 0x4000
	s_addc_u32 s35, s101, 0
	global_load_lds_dwordx4 v136, s[34:35]
	s_add_u32 m0, s28, 0x4c00
	s_add_u32 s34, s100, 0x6000
	s_addc_u32 s35, s101, 0
	global_load_lds_dwordx4 v137, s[34:35]
	s_add_u32 s98, s98, 0x80
	s_addc_u32 s99, s99, 0
	s_add_u32 s100, s100, 0x80
	s_addc_u32 s101, s101, 0
	v_mov_b32_e32 v20, 0
	v_mov_b32_e32 v21, 0
	v_mov_b32_e32 v22, 0
	v_mov_b32_e32 v23, 0
	v_mov_b32_e32 v24, 0
	v_mov_b32_e32 v25, 0
	v_mov_b32_e32 v26, 0
	v_mov_b32_e32 v27, 0
	v_mov_b32_e32 v28, 0
	v_mov_b32_e32 v29, 0
	v_mov_b32_e32 v30, 0
	v_mov_b32_e32 v31, 0
	v_mov_b32_e32 v32, 0
	v_mov_b32_e32 v33, 0
	v_mov_b32_e32 v34, 0
	v_mov_b32_e32 v35, 0
	v_mov_b32_e32 v36, 0
	v_mov_b32_e32 v37, 0
	v_mov_b32_e32 v38, 0
	v_mov_b32_e32 v39, 0
	v_mov_b32_e32 v40, 0
	v_mov_b32_e32 v41, 0
	v_mov_b32_e32 v42, 0
	v_mov_b32_e32 v43, 0
	v_mov_b32_e32 v44, 0
	v_mov_b32_e32 v45, 0
	v_mov_b32_e32 v46, 0
	v_mov_b32_e32 v47, 0
	v_mov_b32_e32 v48, 0
	v_mov_b32_e32 v49, 0
	v_mov_b32_e32 v50, 0
	v_mov_b32_e32 v51, 0
	v_mov_b32_e32 v52, 0
	v_mov_b32_e32 v53, 0
	v_mov_b32_e32 v54, 0
	v_mov_b32_e32 v55, 0
	v_mov_b32_e32 v56, 0
	v_mov_b32_e32 v57, 0
	v_mov_b32_e32 v58, 0
	v_mov_b32_e32 v59, 0
	v_mov_b32_e32 v60, 0
	v_mov_b32_e32 v61, 0
	v_mov_b32_e32 v62, 0
	v_mov_b32_e32 v63, 0
	v_mov_b32_e32 v64, 0
	v_mov_b32_e32 v65, 0
	v_mov_b32_e32 v66, 0
	v_mov_b32_e32 v67, 0
	v_mov_b32_e32 v84, 0
	v_mov_b32_e32 v85, 0
	v_mov_b32_e32 v86, 0
	v_mov_b32_e32 v87, 0
	v_mov_b32_e32 v88, 0
	v_mov_b32_e32 v89, 0
	v_mov_b32_e32 v90, 0
	v_mov_b32_e32 v91, 0
	v_mov_b32_e32 v92, 0
	v_mov_b32_e32 v93, 0
	v_mov_b32_e32 v94, 0
	v_mov_b32_e32 v95, 0
	v_mov_b32_e32 v96, 0
	v_mov_b32_e32 v97, 0
	v_mov_b32_e32 v98, 0
	v_mov_b32_e32 v99, 0
	s_mov_b32 s57, 0
.Lmbk_loop:
	s_waitcnt vmcnt(0)
	s_barrier
	ds_read_b128 v[156:159], v142 offset:0
	ds_read_b128 v[148:151], v138 offset:0
	ds_read_b128 v[152:155], v138 offset:4096
	ds_read_b128 v[160:163], v142 offset:4096
	s_waitcnt lgkmcnt(2)
	v_mfma_f32_32x32x16_bf16 v[84:99], v[156:159], v[148:151], v[84:99]
	s_add_u32 m0, s28, 0x8000
	s_nop 0
	global_load_lds_dwordx4 v134, s[98:99]
	ds_read_b128 v[172:175], v143 offset:0
	ds_read_b128 v[164:167], v139 offset:0
	s_waitcnt lgkmcnt(3)
	v_mfma_f32_32x32x16_bf16 v[36:51], v[156:159], v[152:155], v[36:51]
	s_add_u32 m0, s28, 0x8400
	s_add_u32 s34, s98, s0
	s_addc_u32 s35, s99, 0
	global_load_lds_dwordx4 v135, s[34:35]
	ds_read_b128 v[168:171], v139 offset:4096
	s_waitcnt lgkmcnt(3)
	v_mfma_f32_32x32x16_bf16 v[52:67], v[160:163], v[148:151], v[52:67]
	s_add_u32 m0, s28, 0x8800
	s_add_u32 s34, s34, s0
	s_addc_u32 s35, s35, 0
	global_load_lds_dwordx4 v134, s[34:35]
	ds_read_b128 v[176:179], v143 offset:4096
	v_mfma_f32_32x32x16_bf16 v[20:35], v[160:163], v[152:155], v[20:35]
	s_add_u32 m0, s28, 0x8c00
	s_add_u32 s34, s34, s0
	s_addc_u32 s35, s35, 0
	global_load_lds_dwordx4 v135, s[34:35]
	s_waitcnt lgkmcnt(2)
	v_mfma_f32_32x32x16_bf16 v[84:99], v[172:175], v[164:167], v[84:99]
	s_add_u32 m0, s28, 0xd840
	s_nop 0
	global_load_lds_dwordx4 v136, s[100:101]
	ds_read_b128 v[156:159], v144 offset:0
	ds_read_b128 v[148:151], v140 offset:0
	s_waitcnt lgkmcnt(3)
; template <int NI, bool DEEP = true>
; DEV void gemm_tile(f32x16 (&acc)[2][NI], const bf16* __restrict__ A, int lda, const bf16* __restrict__ Bt, int ldb,
;                    int K, bf16* sA, bf16* sB) {
;     ...
;   G_LOAD(ra0, rb0, 0)
;   if (DEEP) {
;     if (64 < K) G_LOAD(ra1, rb1, 64)
;     for (int k0 = 0; k0 < K; k0 += 128) {
;       G_STEP(ra0, rb0, k0 + 128)
;       if (k0 + 64 < K) G_STEP(ra1, rb1, k0 + 192)
;     }
;   } else {
;     for (int k0 = 0; k0 < K; k0 += 64) G_STEP(ra0, rb0, k0 + 64)
	v_mfma_f32_32x32x16_bf16 v[36:51], v[172:175], v[168:171], v[36:51]
	s_add_u32 m0, s28, 0xdc40
	s_add_u32 s34, s100, 0x2000
	s_addc_u32 s35, s101, 0
	global_load_lds_dwordx4 v137, s[34:35]
	ds_read_b128 v[152:155], v140 offset:4096
	s_waitcnt lgkmcnt(3)
	v_mfma_f32_32x32x16_bf16 v[52:67], v[176:179], v[164:167], v[52:67]
	s_add_u32 m0, s28, 0xe040
	s_add_u32 s34, s100, 0x4000
	s_addc_u32 s35, s101, 0
	global_load_lds_dwordx4 v136, s[34:35]
	ds_read_b128 v[160:163], v144 offset:4096
	v_mfma_f32_32x32x16_bf16 v[20:35], v[176:179], v[168:171], v[20:35]
	s_add_u32 m0, s28, 0xe440
	s_add_u32 s34, s100, 0x6000
	s_addc_u32 s35, s101, 0
	global_load_lds_dwordx4 v137, s[34:35]
	s_waitcnt lgkmcnt(2)
	v_mfma_f32_32x32x16_bf16 v[84:99], v[156:159], v[148:151], v[84:99]
	s_add_u32 s98, s98, 0x80
	s_addc_u32 s99, s99, 0
	s_add_u32 s100, s100, 0x80
	s_addc_u32 s101, s101, 0
	ds_read_b128 v[172:175], v145 offset:0
	ds_read_b128 v[164:167], v141 offset:0
	s_waitcnt lgkmcnt(3)
	v_mfma_f32_32x32x16_bf16 v[36:51], v[156:159], v[152:155], v[36:51]
	ds_read_b128 v[168:171], v141 offset:4096
	s_waitcnt lgkmcnt(3)
	v_mfma_f32_32x32x16_bf16 v[52:67], v[160:163], v[148:151], v[52:67]
	ds_read_b128 v[176:179], v145 offset:4096
	v_mfma_f32_32x32x16_bf16 v[20:35], v[160:163], v[152:155], v[20:35]
	s_waitcnt lgkmcnt(2)
	v_mfma_f32_32x32x16_bf16 v[84:99], v[172:175], v[164:167], v[84:99]
	s_waitcnt lgkmcnt(1)
	v_mfma_f32_32x32x16_bf16 v[36:51], v[172:175], v[168:171], v[36:51]
	s_waitcnt lgkmcnt(0)
	v_mfma_f32_32x32x16_bf16 v[52:67], v[176:179], v[164:167], v[52:67]
	v_mfma_f32_32x32x16_bf16 v[20:35], v[176:179], v[168:171], v[20:35]
	s_waitcnt vmcnt(0)
	s_barrier
	s_cmp_eq_u32 s57, 3
	s_cbranch_scc1 .Lmbk_nodma
	ds_read_b128 v[156:159], v142 offset:38976
	ds_read_b128 v[148:151], v138 offset:32768
	ds_read_b128 v[152:155], v138 offset:36864
	ds_read_b128 v[160:163], v142 offset:43072
	s_waitcnt lgkmcnt(2)
	v_mfma_f32_32x32x16_bf16 v[84:99], v[156:159], v[148:151], v[84:99]
	s_add_u32 m0, s28, 0x0
	s_nop 0
	global_load_lds_dwordx4 v134, s[98:99]
	ds_read_b128 v[172:175], v143 offset:38976
	ds_read_b128 v[164:167], v139 offset:32768
	s_waitcnt lgkmcnt(3)
	v_mfma_f32_32x32x16_bf16 v[36:51], v[156:159], v[152:155], v[36:51]
	s_add_u32 m0, s28, 0x400
	s_add_u32 s34, s98, s0
	s_addc_u32 s35, s99, 0
	global_load_lds_dwordx4 v135, s[34:35]
	ds_read_b128 v[168:171], v139 offset:36864
	s_waitcnt lgkmcnt(3)
	v_mfma_f32_32x32x16_bf16 v[52:67], v[160:163], v[148:151], v[52:67]
	s_add_u32 m0, s28, 0x800
	s_add_u32 s34, s34, s0
	s_addc_u32 s35, s35, 0
	global_load_lds_dwordx4 v134, s[34:35]
	ds_read_b128 v[176:179], v143 offset:43072
	v_mfma_f32_32x32x16_bf16 v[20:35], v[160:163], v[152:155], v[20:35]
	s_add_u32 m0, s28, 0xc00
	s_add_u32 s34, s34, s0
	s_addc_u32 s35, s35, 0
	global_load_lds_dwordx4 v135, s[34:35]
	s_waitcnt lgkmcnt(2)
	v_mfma_f32_32x32x16_bf16 v[84:99], v[172:175], v[164:167], v[84:99]
	s_add_u32 m0, s28, 0x4000
	s_nop 0
	global_load_lds_dwordx4 v136, s[100:101]
	ds_read_b128 v[156:159], v144 offset:38976
	ds_read_b128 v[148:151], v140 offset:32768
	s_waitcnt lgkmcnt(3)
	v_mfma_f32_32x32x16_bf16 v[36:51], v[172:175], v[168:171], v[36:51]
	s_add_u32 m0, s28, 0x4400
	s_add_u32 s34, s100, 0x2000
	s_addc_u32 s35, s101, 0
	global_load_lds_dwordx4 v137, s[34:35]
	ds_read_b128 v[152:155], v140 offset:36864
	s_waitcnt lgkmcnt(3)
	v_mfma_f32_32x32x16_bf16 v[52:67], v[176:179], v[164:167], v[52:67]
	s_add_u32 m0, s28, 0x4800
	s_add_u32 s34, s100, 0x4000
	s_addc_u32 s35, s101, 0
	global_load_lds_dwordx4 v136, s[34:35]
	ds_read_b128 v[160:163], v144 offset:43072
	v_mfma_f32_32x32x16_bf16 v[20:35], v[176:179], v[168:171], v[20:35]
	s_add_u32 m0, s28, 0x4c00
	s_add_u32 s34, s100, 0x6000
	s_addc_u32 s35, s101, 0
	global_load_lds_dwordx4 v137, s[34:35]
	s_waitcnt lgkmcnt(2)
	v_mfma_f32_32x32x16_bf16 v[84:99], v[156:159], v[148:151], v[84:99]
	s_add_u32 s98, s98, 0x80
	s_addc_u32 s99, s99, 0
	s_add_u32 s100, s100, 0x80
	s_addc_u32 s101, s101, 0
	ds_read_b128 v[172:175], v145 offset:38976
	ds_read_b128 v[164:167], v141 offset:32768
	s_waitcnt lgkmcnt(3)
	v_mfma_f32_32x32x16_bf16 v[36:51], v[156:159], v[152:155], v[36:51]
	ds_read_b128 v[168:171], v141 offset:36864
	s_waitcnt lgkmcnt(3)
	v_mfma_f32_32x32x16_bf16 v[52:67], v[160:163], v[148:151], v[52:67]
	ds_read_b128 v[176:179], v145 offset:43072
	v_mfma_f32_32x32x16_bf16 v[20:35], v[160:163], v[152:155], v[20:35]
	s_waitcnt lgkmcnt(2)
	v_mfma_f32_32x32x16_bf16 v[84:99], v[172:175], v[164:167], v[84:99]
	s_waitcnt lgkmcnt(1)
	v_mfma_f32_32x32x16_bf16 v[36:51], v[172:175], v[168:171], v[36:51]
	s_waitcnt lgkmcnt(0)
	v_mfma_f32_32x32x16_bf16 v[52:67], v[176:179], v[164:167], v[52:67]
	v_mfma_f32_32x32x16_bf16 v[20:35], v[176:179], v[168:171], v[20:35]
	s_branch .Lmbk_next
.Lmbk_nodma:
	ds_read_b128 v[156:159], v142 offset:38976
	ds_read_b128 v[148:151], v138 offset:32768
	ds_read_b128 v[152:155], v138 offset:36864
	ds_read_b128 v[160:163], v142 offset:43072
	s_waitcnt lgkmcnt(2)
	v_mfma_f32_32x32x16_bf16 v[84:99], v[156:159], v[148:151], v[84:99]
	ds_read_b128 v[172:175], v143 offset:38976
	ds_read_b128 v[164:167], v139 offset:32768
	s_waitcnt lgkmcnt(3)
	v_mfma_f32_32x32x16_bf16 v[36:51], v[156:159], v[152:155], v[36:51]
	ds_read_b128 v[168:171], v139 offset:36864
	s_waitcnt lgkmcnt(3)
	v_mfma_f32_32x32x16_bf16 v[52:67], v[160:163], v[148:151], v[52:67]
	ds_read_b128 v[176:179], v143 offset:43072
	v_mfma_f32_32x32x16_bf16 v[20:35], v[160:163], v[152:155], v[20:35]
	s_waitcnt lgkmcnt(2)
	v_mfma_f32_32x32x16_bf16 v[84:99], v[172:175], v[164:167], v[84:99]
	ds_read_b128 v[156:159], v144 offset:38976
	ds_read_b128 v[148:151], v140 offset:32768
	s_waitcnt lgkmcnt(3)
	v_mfma_f32_32x32x16_bf16 v[36:51], v[172:175], v[168:171], v[36:51]
	ds_read_b128 v[152:155], v140 offset:36864
	s_waitcnt lgkmcnt(3)
	v_mfma_f32_32x32x16_bf16 v[52:67], v[176:179], v[164:167], v[52:67]
	ds_read_b128 v[160:163], v144 offset:43072
	v_mfma_f32_32x32x16_bf16 v[20:35], v[176:179], v[168:171], v[20:35]
	s_waitcnt lgkmcnt(2)
	v_mfma_f32_32x32x16_bf16 v[84:99], v[156:159], v[148:151], v[84:99]
	ds_read_b128 v[172:175], v145 offset:38976
	ds_read_b128 v[164:167], v141 offset:32768
	s_waitcnt lgkmcnt(3)
	v_mfma_f32_32x32x16_bf16 v[36:51], v[156:159], v[152:155], v[36:51]
	ds_read_b128 v[168:171], v141 offset:36864
	s_waitcnt lgkmcnt(3)
	v_mfma_f32_32x32x16_bf16 v[52:67], v[160:163], v[148:151], v[52:67]
	ds_read_b128 v[176:179], v145 offset:43072
	v_mfma_f32_32x32x16_bf16 v[20:35], v[160:163], v[152:155], v[20:35]
	s_waitcnt lgkmcnt(2)
	v_mfma_f32_32x32x16_bf16 v[84:99], v[172:175], v[164:167], v[84:99]
	s_waitcnt lgkmcnt(1)
	v_mfma_f32_32x32x16_bf16 v[36:51], v[172:175], v[168:171], v[36:51]
	s_waitcnt lgkmcnt(0)
	v_mfma_f32_32x32x16_bf16 v[52:67], v[176:179], v[164:167], v[52:67]
	v_mfma_f32_32x32x16_bf16 v[20:35], v[176:179], v[168:171], v[20:35]
.Lmbk_next:
	s_add_i32 s57, s57, 1
	s_cmp_lt_u32 s57, 4
	s_cbranch_scc1 .Lmbk_loop
	s_nop 7
	s_nop 7
